# dilated loop: band masks built from a per-lane 32-key bit mask (bfe+bfi per element) on top of straight-line descriptors and fall-through layout
# baseline (speedup 1.0000x reference)
.LBB0_697:
	s_and_b64 s[16:17], exec, s[14:15]
	s_cselect_b32 s16, s50, -1
	s_add_i32 s16, s16, s70
	s_cmp_lt_u32 s16, 3
	s_cselect_b64 s[16:17], -1, 0
	v_add_u32_e32 v18, s71, v198
	s_and_b64 s[0:1], s[0:1], s[16:17]
	v_sub_u32_e32 v19, v0, v18
	s_mov_b64 s[16:17], -1
	s_and_b64 vcc, exec, s[0:1]
	s_cbranch_vccnz .Ldd_aonA
	s_waitcnt lgkmcnt(8)
	v_add_u32_e32 v228, 0xffffff80, v19
	v_add_u32_e32 v229, 1, v19
	v_med3_i32 v228, v228, 0, 32
	v_med3_i32 v229, v229, 0, 32
	v_lshlrev_b64 v[230:231], v228, -1
	v_lshlrev_b64 v[232:233], v229, -1
	v_xor_b32_e32 v234, 0x80000000, v209
	v_bfi_b32 v230, v232, 0, v230
	v_bfe_i32 v0, v230, 0, 1
	v_bfe_i32 v1, v230, 1, 1
	v_bfe_i32 v2, v230, 2, 1
	v_bfe_i32 v3, v230, 3, 1
	v_bfi_b32 v0, v0, v234, v211
	v_bfi_b32 v1, v1, v234, v211
	v_bfi_b32 v2, v2, v234, v211
	v_bfi_b32 v3, v3, v234, v211
	v_bfe_i32 v4, v230, 8, 1
	v_bfe_i32 v5, v230, 9, 1
	v_bfe_i32 v6, v230, 10, 1
	v_bfe_i32 v7, v230, 11, 1
	v_bfi_b32 v4, v4, v234, v211
	v_bfi_b32 v5, v5, v234, v211
	v_bfi_b32 v6, v6, v234, v211
	v_bfi_b32 v7, v7, v234, v211
	v_bfe_i32 v8, v230, 16, 1
	v_bfe_i32 v9, v230, 17, 1
	v_bfe_i32 v10, v230, 18, 1
	v_bfe_i32 v11, v230, 19, 1
	v_bfi_b32 v8, v8, v234, v211
	v_bfi_b32 v9, v9, v234, v211
	v_bfi_b32 v10, v10, v234, v211
	v_bfi_b32 v11, v11, v234, v211
	v_bfe_i32 v12, v230, 24, 1
	v_bfe_i32 v13, v230, 25, 1
	v_bfe_i32 v14, v230, 26, 1
	v_bfe_i32 v15, v230, 27, 1
	v_bfi_b32 v12, v12, v234, v211
	v_bfi_b32 v13, v13, v234, v211
	v_bfi_b32 v14, v14, v234, v211
	v_bfi_b32 v15, v15, v234, v211
.LBB0_701:
	v_sub_u32_e32 v16, v16, v18
	s_and_b64 vcc, exec, s[0:1]
	s_cbranch_vccnz .Ldd_aonB
	v_add_u32_e32 v236, 0xffffff80, v16
	v_add_u32_e32 v237, 1, v16
	v_med3_i32 v236, v236, 0, 32
	v_med3_i32 v237, v237, 0, 32
	v_lshlrev_b64 v[238:239], v236, -1
	v_lshlrev_b64 v[240:241], v237, -1
	v_xor_b32_e32 v242, 0x80000000, v226
	v_bfi_b32 v238, v240, 0, v238
	v_bfe_i32 v112, v238, 0, 1
	v_bfe_i32 v113, v238, 1, 1
	v_bfe_i32 v114, v238, 2, 1
	v_bfe_i32 v115, v238, 3, 1
	v_bfi_b32 v112, v112, v242, v211
	v_bfi_b32 v113, v113, v242, v211
	v_bfi_b32 v114, v114, v242, v211
	v_bfi_b32 v115, v115, v242, v211
	v_bfe_i32 v116, v238, 8, 1
	v_bfe_i32 v117, v238, 9, 1
	v_bfe_i32 v118, v238, 10, 1
	v_bfe_i32 v119, v238, 11, 1
	v_bfi_b32 v116, v116, v242, v211
	v_bfi_b32 v117, v117, v242, v211
	v_bfi_b32 v118, v118, v242, v211
	v_bfi_b32 v119, v119, v242, v211
	v_bfe_i32 v120, v238, 16, 1
	v_bfe_i32 v121, v238, 17, 1
	v_bfe_i32 v122, v238, 18, 1
	v_bfe_i32 v123, v238, 19, 1
	v_bfi_b32 v120, v120, v242, v211
	v_bfi_b32 v121, v121, v242, v211
	v_bfi_b32 v122, v122, v242, v211
	v_bfi_b32 v123, v123, v242, v211
	v_bfe_i32 v124, v238, 24, 1
	v_bfe_i32 v125, v238, 25, 1
	v_bfe_i32 v126, v238, 26, 1
	v_bfe_i32 v127, v238, 27, 1
	v_bfi_b32 v124, v124, v242, v211
	v_bfi_b32 v125, v125, v242, v211
	v_bfi_b32 v126, v126, v242, v211
	v_bfi_b32 v127, v127, v242, v211
